# baseline (speedup 1.0000x reference)
; #define LAS __attribute__((address_space(3)))
; __device__ __forceinline__ unsigned pk2(float lo, float hi) { return pg8::cvt_pk_bf16(lo, hi); }
; __device__ __forceinline__ void transpose_item(const float* W, int K, int N, bf16* WT, int k0, int n0, int drow, LAS float* scr, int lane) {
;     f32x4 v[8];
; #pragma unroll
;     for (int i = 0; i < 8; ++i) v[i] = *(const f32x4*)(W + (size_t)(k0 + 8 * i + (lane >> 3)) * N + n0 + 4 * (lane & 7));
; #pragma unroll
;     for (int i = 0; i < 8; ++i) { LAS float* d = scr + (8 * i + (lane >> 3)) * 33 + 4 * (lane & 7); d[0] = v[i].x; d[1] = v[i].y; d[2] = v[i].z; d[3] = v[i].w; }
;     asm volatile("s_waitcnt lgkmcnt(0)" ::: "memory");
;     const int c = lane & 7;
; #pragma unroll
;     for (int j = 0; j < 4; ++j) { const int n = (lane >> 3) + 8 * j; const LAS float* s = scr + (8 * c) * 33 + n;
;         u32x4 o; o.x = pk2(s[0 * 33], s[1 * 33]); o.y = pk2(s[2 * 33], s[3 * 33]); o.z = pk2(s[4 * 33], s[5 * 33]); o.w = pk2(s[6 * 33], s[7 * 33]);
;         *(u32x4*)(WT + (size_t)(drow + n) * K + k0 + 8 * c) = o; }
;     asm volatile("s_waitcnt lgkmcnt(0)" ::: "memory");
; }
.LBB0_520:
	s_ashr_i32 s55, s54, 31
	s_lshl_b32 s22, s25, 6
	s_lshl_b64 s[24:25], s[54:55], 2
	v_or_b32_e32 v5, s22, v1
	s_add_u32 s24, s48, s24
	s_addc_u32 s25, s49, s25
	s_ashr_i32 s23, s22, 31
	v_or_b32_e32 v18, 16, v5
	v_or_b32_e32 v26, 32, v5
	v_lshl_add_u64 v[38:39], s[24:25], 0, v[148:149]
	s_mul_i32 s5, s52, s23
	v_mul_lo_u32 v12, s53, v5
	v_mad_u64_u32 v[10:11], s[24:25], s52, v5, 0
	v_mul_lo_u32 v20, s53, v18
	v_mad_u64_u32 v[18:19], s[24:25], s52, v18, 0
	v_mul_lo_u32 v28, s53, v26
	v_mad_u64_u32 v[26:27], s[24:25], s52, v26, 0
	v_add3_u32 v11, v11, s5, v12
	v_or_b32_e32 v12, 8, v5
	v_add3_u32 v19, v19, s5, v20
	v_or_b32_e32 v20, 24, v5
	v_add3_u32 v27, v27, s5, v28
	v_or_b32_e32 v28, 40, v5
	v_mul_lo_u32 v14, s53, v12
	v_mad_u64_u32 v[12:13], s[24:25], s52, v12, 0
	v_mul_lo_u32 v22, s53, v20
	v_mad_u64_u32 v[20:21], s[24:25], s52, v20, 0
	v_mul_lo_u32 v30, s53, v28
	v_mad_u64_u32 v[28:29], s[24:25], s52, v28, 0
	v_or_b32_e32 v34, 48, v5
	v_add3_u32 v13, v13, s5, v14
	v_add3_u32 v21, v21, s5, v22
	v_add3_u32 v29, v29, s5, v30
	v_mul_lo_u32 v36, s53, v34
	v_mad_u64_u32 v[34:35], s[24:25], s52, v34, 0
	v_or_b32_e32 v5, 56, v5
	v_lshl_add_u64 v[10:11], v[10:11], 2, v[38:39]
	v_lshl_add_u64 v[14:15], v[12:13], 2, v[38:39]
	v_lshl_add_u64 v[18:19], v[18:19], 2, v[38:39]
	v_lshl_add_u64 v[22:23], v[20:21], 2, v[38:39]
	v_lshl_add_u64 v[26:27], v[26:27], 2, v[38:39]
	v_lshl_add_u64 v[30:31], v[28:29], 2, v[38:39]
	v_add3_u32 v35, v35, s5, v36
	v_mul_lo_u32 v42, s53, v5
	v_mad_u64_u32 v[40:41], s[24:25], s52, v5, 0
	global_load_dwordx4 v[10:13], v[10:11], off nt
	s_nop 0
	global_load_dwordx4 v[14:17], v[14:15], off nt
	s_nop 0
	global_load_dwordx4 v[18:21], v[18:19], off nt
	s_nop 0
	global_load_dwordx4 v[22:25], v[22:23], off nt
	s_nop 0
	global_load_dwordx4 v[26:29], v[26:27], off nt
	s_nop 0
	global_load_dwordx4 v[30:33], v[30:31], off nt
	v_lshl_add_u64 v[34:35], v[34:35], 2, v[38:39]
	v_add3_u32 v41, v41, s5, v42
	global_load_dwordx4 v[34:37], v[34:35], off nt
	v_lshl_add_u64 v[38:39], v[40:41], 2, v[38:39]
	global_load_dwordx4 v[38:41], v[38:39], off nt
	v_add_u32_e32 v5, 0x420, v9
	v_add_u32_e32 v42, 0x428, v9
	v_add_u32_e32 v43, 0x840, v9
	v_add_u32_e32 v44, 0x848, v9
	v_add_u32_e32 v45, 0xc60, v9
	v_add_u32_e32 v46, 0xc68, v9
	v_add_u32_e32 v47, 0x1080, v9
	v_add_u32_e32 v48, 0x1088, v9
	v_add_u32_e32 v49, 0x14a0, v9
	v_add_u32_e32 v50, 0x14a8, v9
	v_add_u32_e32 v51, 0x18c0, v9
	s_lshl_b64 s[22:23], s[22:23], 1
	s_waitcnt lgkmcnt(0)
	s_add_u32 s22, s42, s22
	s_addc_u32 s23, s43, s23
	s_add_i32 s19, s19, s20
	s_add_i32 s9, s9, s11
	s_cmp_gt_i32 s19, 0x16eff
	s_waitcnt vmcnt(7)
	ds_write2_b32 v9, v10, v11 offset1:1
	ds_write2_b32 v9, v12, v13 offset0:2 offset1:3
	s_waitcnt vmcnt(6)
	ds_write2_b32 v5, v14, v15 offset1:1
	ds_write2_b32 v42, v16, v17 offset1:1
	s_waitcnt vmcnt(5)
	ds_write2_b32 v43, v18, v19 offset1:1
	ds_write2_b32 v44, v20, v21 offset1:1
	s_waitcnt vmcnt(4)
	ds_write2_b32 v45, v22, v23 offset1:1
	ds_write2_b32 v46, v24, v25 offset1:1
	s_waitcnt vmcnt(3)
	ds_write2_b32 v47, v26, v27 offset1:1
	ds_write2_b32 v48, v28, v29 offset1:1
	s_waitcnt vmcnt(2)
	ds_write2_b32 v49, v30, v31 offset1:1
	ds_write2_b32 v50, v32, v33 offset1:1
	s_waitcnt vmcnt(1)
	ds_write2_b32 v51, v34, v35 offset1:1
	v_add_u32_e32 v5, 0x18c8, v9
	v_add_u32_e32 v18, s21, v1
	ds_write2_b32 v5, v36, v37 offset1:1
	v_add_u32_e32 v5, 0x1ce0, v9
	s_waitcnt vmcnt(0)
	ds_write2_b32 v5, v38, v39 offset1:1
	v_add_u32_e32 v5, 0x1ce8, v9
	ds_write2_b32 v5, v40, v41 offset1:1
	s_waitcnt lgkmcnt(0)
	ds_read2_b32 v[10:11], v8 offset1:33
	v_mov_b32_e32 v5, v149
	v_ashrrev_i32_e32 v19, 31, v18
	s_waitcnt lgkmcnt(0)
	v_cvt_pk_bf16_f32 v10, v10, v11
	ds_read2_b32 v[12:13], v8 offset0:66 offset1:99
	v_lshl_add_u64 v[16:17], s[22:23], 0, v[4:5]
	v_mul_lo_u32 v5, s40, v19
	v_mul_lo_u32 v20, s41, v18
	v_mad_u64_u32 v[18:19], s[22:23], s40, v18, 0
	s_waitcnt lgkmcnt(0)
	v_cvt_pk_bf16_f32 v11, v12, v13
	ds_read2_b32 v[12:13], v8 offset0:132 offset1:165
	v_add3_u32 v19, v19, v5, v20
	s_waitcnt lgkmcnt(0)
	v_cvt_pk_bf16_f32 v12, v12, v13
	ds_read2_b32 v[14:15], v8 offset0:198 offset1:231
	s_waitcnt lgkmcnt(0)
	v_cvt_pk_bf16_f32 v13, v14, v15
	v_lshl_add_u64 v[18:19], v[18:19], 1, v[16:17]
	ds_read2_b32 v[14:15], v8 offset0:8 offset1:41
	global_store_dwordx4 v[18:19], v[10:13], off nt
	v_add_u32_e32 v5, s21, v3
	v_mul_lo_u32 v20, s41, v5
	s_waitcnt lgkmcnt(0)
	v_cvt_pk_bf16_f32 v10, v14, v15
	ds_read2_b32 v[12:13], v8 offset0:74 offset1:107
	s_waitcnt lgkmcnt(0)
	v_cvt_pk_bf16_f32 v11, v12, v13
	ds_read2_b32 v[12:13], v8 offset0:140 offset1:173
	s_waitcnt lgkmcnt(0)
	v_cvt_pk_bf16_f32 v12, v12, v13
	v_ashrrev_i32_e32 v13, 31, v5
	v_mul_lo_u32 v21, s40, v13
	v_mad_u64_u32 v[18:19], s[22:23], s40, v5, 0
	v_add3_u32 v19, v19, v21, v20
	v_add_u32_e32 v5, s21, v6
	ds_read2_b32 v[14:15], v8 offset0:206 offset1:239
	s_waitcnt lgkmcnt(0)
	v_cvt_pk_bf16_f32 v13, v14, v15
	v_lshl_add_u64 v[18:19], v[18:19], 1, v[16:17]
	v_ashrrev_i32_e32 v20, 31, v5
	ds_read2_b32 v[14:15], v8 offset0:16 offset1:49
	global_store_dwordx4 v[18:19], v[10:13], off nt
	v_mul_lo_u32 v21, s41, v5
	v_mad_u64_u32 v[18:19], s[22:23], s40, v5, 0
	s_waitcnt lgkmcnt(0)
	v_cvt_pk_bf16_f32 v10, v14, v15
	ds_read2_b32 v[12:13], v8 offset0:82 offset1:115
	v_mul_lo_u32 v5, s40, v20
	s_waitcnt lgkmcnt(0)
	v_cvt_pk_bf16_f32 v11, v12, v13
	ds_read2_b32 v[12:13], v8 offset0:148 offset1:181
	v_add3_u32 v19, v19, v5, v21
	s_waitcnt lgkmcnt(0)
	v_cvt_pk_bf16_f32 v12, v12, v13
	ds_read2_b32 v[14:15], v8 offset0:214 offset1:247
	v_lshl_add_u64 v[18:19], v[18:19], 1, v[16:17]
	v_add_u32_e32 v5, s21, v7
	s_waitcnt lgkmcnt(0)
	v_cvt_pk_bf16_f32 v13, v14, v15
	ds_read2_b32 v[14:15], v8 offset0:24 offset1:57
	global_store_dwordx4 v[18:19], v[10:13], off nt
	v_ashrrev_i32_e32 v18, 31, v5
	v_mul_lo_u32 v20, s41, v5
	s_waitcnt lgkmcnt(0)
	v_cvt_pk_bf16_f32 v10, v14, v15
	v_mad_u64_u32 v[14:15], s[22:23], s40, v5, 0
	v_mul_lo_u32 v5, s40, v18
	ds_read2_b32 v[12:13], v8 offset0:90 offset1:123
	v_add3_u32 v15, v15, v5, v20
	s_waitcnt lgkmcnt(0)
	v_cvt_pk_bf16_f32 v11, v12, v13
	ds_read2_b32 v[12:13], v8 offset0:156 offset1:189
	v_lshl_add_u64 v[14:15], v[14:15], 1, v[16:17]
	s_waitcnt lgkmcnt(0)
	v_cvt_pk_bf16_f32 v12, v12, v13
	ds_read2_b32 v[18:19], v8 offset0:222 offset1:255
	s_waitcnt lgkmcnt(0)
	v_cvt_pk_bf16_f32 v13, v18, v19
	global_store_dwordx4 v[14:15], v[10:13], off nt
	s_waitcnt lgkmcnt(0)
	s_cbranch_scc1 .LBB0_548
